# v69 + P4 y_prompt epilogue stores marked sc1 (write-through, line dropped from L2: nothing re-reads y; shorter end-of-kernel drain)
# speedup vs baseline: 1.0014x; 1.0014x over previous
.LBB0_3637:
	s_or_b64 exec, exec, s[2:3]
	s_lshl_b32 s0, s12, 8
	s_or_b32 s0, s0, s33
	v_or_b32_e32 v128, s0, v182
	v_ashrrev_i32_e32 v129, 31, v128
	v_lshlrev_b64 v[160:161], 2, v[128:129]
	s_waitcnt lgkmcnt(0)
	s_barrier
	v_lshl_add_u64 v[128:129], s[8:9], 0, v[160:161]
	v_lshl_add_u64 v[132:133], s[10:11], 0, v[160:161]
	global_load_dwordx4 v[152:155], v[132:133], off
	global_load_dwordx4 v[156:159], v[128:129], off
	global_load_dwordx4 v[144:147], v[128:129], off offset:64
	global_load_dwordx4 v[148:151], v[132:133], off offset:64
	global_load_dwordx4 v[136:139], v[132:133], off offset:512
	global_load_dwordx4 v[140:143], v[128:129], off offset:512
	s_nop 0
	global_load_dwordx4 v[128:131], v[128:129], off offset:576
	s_nop 0
	global_load_dwordx4 v[132:135], v[132:133], off offset:576
	v_or_b32_e32 v165, v179, v178
	v_lshl_add_u32 v166, v181, 3, 0
	s_waitcnt lgkmcnt(0)
	v_or_b32_e32 v165, v164, v165
	v_add_u32_e32 v164, 0x2000, v166
	ds_read2_b64 v[166:169], v164 offset1:16
	v_add_u32_e32 v170, v163, v181
	v_ashrrev_i32_e32 v171, 31, v170
	v_lshlrev_b64 v[170:171], 12, v[170:171]
	v_mov_b32_e32 v162, 0x7fc00000
	s_waitcnt lgkmcnt(0)
	v_sub_f32_e32 v107, v107, v166
	v_sub_f32_e32 v106, v106, v166
	v_sub_f32_e32 v105, v105, v166
	v_sub_f32_e32 v104, v104, v166
	v_sub_f32_e32 v111, v111, v166
	v_sub_f32_e32 v110, v110, v166
	v_sub_f32_e32 v109, v109, v166
	v_sub_f32_e32 v108, v108, v166
	v_sub_f32_e32 v95, v95, v166
	v_sub_f32_e32 v94, v94, v166
	v_sub_f32_e32 v93, v93, v166
	v_sub_f32_e32 v92, v92, v166
	v_sub_f32_e32 v99, v99, v166
	v_sub_f32_e32 v98, v98, v166
	v_sub_f32_e32 v97, v97, v166
	v_sub_f32_e32 v96, v96, v166
	v_pk_mul_f32 v[104:105], v[166:167], v[104:105] op_sel:[1,0]
	v_pk_mul_f32 v[106:107], v[166:167], v[106:107] op_sel:[1,0]
	v_lshl_add_u64 v[170:171], s[6:7], 0, v[170:171]
	v_pk_mul_f32 v[108:109], v[166:167], v[108:109] op_sel:[1,0]
	v_pk_mul_f32 v[110:111], v[166:167], v[110:111] op_sel:[1,0]
	v_pk_mul_f32 v[92:93], v[166:167], v[92:93] op_sel:[1,0]
	v_pk_mul_f32 v[94:95], v[166:167], v[94:95] op_sel:[1,0]
	v_pk_mul_f32 v[96:97], v[166:167], v[96:97] op_sel:[1,0]
	v_pk_mul_f32 v[98:99], v[166:167], v[98:99] op_sel:[1,0]
	v_cmp_ne_u32_e32 vcc, 0, v165
	v_add_u32_e32 v178, v163, v180
	v_lshl_add_u64 v[170:171], v[170:171], 0, v[160:161]
	v_sub_f32_e32 v115, v115, v168
	v_sub_f32_e32 v114, v114, v168
	v_sub_f32_e32 v113, v113, v168
	v_sub_f32_e32 v112, v112, v168
	v_pk_mul_f32 v[112:113], v[168:169], v[112:113] op_sel:[1,0]
	v_ashrrev_i32_e32 v179, 31, v178
	v_sub_f32_e32 v79, v79, v168
	v_sub_f32_e32 v78, v78, v168
	v_sub_f32_e32 v77, v77, v168
	v_sub_f32_e32 v76, v76, v168
	v_pk_mul_f32 v[76:77], v[168:169], v[76:77] op_sel:[1,0]
	v_pk_mul_f32 v[78:79], v[168:169], v[78:79] op_sel:[1,0]
	v_sub_f32_e32 v67, v67, v168
	v_sub_f32_e32 v66, v66, v168
	v_sub_f32_e32 v65, v65, v168
	v_sub_f32_e32 v64, v64, v168
	v_sub_f32_e32 v87, v87, v168
	v_sub_f32_e32 v86, v86, v168
	v_sub_f32_e32 v85, v85, v168
	v_sub_f32_e32 v84, v84, v168
	v_pk_mul_f32 v[64:65], v[168:169], v[64:65] op_sel:[1,0]
	v_pk_mul_f32 v[66:67], v[168:169], v[66:67] op_sel:[1,0]
	v_pk_mul_f32 v[84:85], v[168:169], v[84:85] op_sel:[1,0]
	v_pk_mul_f32 v[86:87], v[168:169], v[86:87] op_sel:[1,0]
	s_waitcnt vmcnt(0)
	v_pk_fma_f32 v[106:107], v[158:159], v[106:107], v[154:155]
	v_pk_fma_f32 v[104:105], v[156:157], v[104:105], v[152:153]
	v_pk_fma_f32 v[110:111], v[146:147], v[110:111], v[150:151]
	v_pk_fma_f32 v[108:109], v[144:145], v[108:109], v[148:149]
	v_pk_fma_f32 v[166:167], v[142:143], v[94:95], v[138:139]
	v_pk_fma_f32 v[180:181], v[140:141], v[92:93], v[136:137]
	v_pk_fma_f32 v[182:183], v[130:131], v[98:99], v[134:135]
	v_pk_fma_f32 v[184:185], v[128:129], v[96:97], v[132:133]
	v_cndmask_b32_e32 v95, v107, v162, vcc
	v_cndmask_b32_e32 v94, v106, v162, vcc
	v_cndmask_b32_e32 v93, v105, v162, vcc
	v_cndmask_b32_e32 v92, v104, v162, vcc
	v_cndmask_b32_e32 v99, v111, v162, vcc
	v_cndmask_b32_e32 v98, v110, v162, vcc
	v_cndmask_b32_e32 v97, v109, v162, vcc
	v_cndmask_b32_e32 v96, v108, v162, vcc
	v_cndmask_b32_e32 v107, v167, v162, vcc
	v_cndmask_b32_e32 v106, v166, v162, vcc
	v_cndmask_b32_e32 v105, v181, v162, vcc
	v_cndmask_b32_e32 v104, v180, v162, vcc
	v_cndmask_b32_e32 v111, v183, v162, vcc
	v_cndmask_b32_e32 v110, v182, v162, vcc
	v_cndmask_b32_e32 v109, v185, v162, vcc
	v_cndmask_b32_e32 v108, v184, v162, vcc
	global_store_dwordx4 v[170:171], v[92:95], off sc1
	global_store_dwordx4 v[170:171], v[96:99], off offset:64 sc1
	global_store_dwordx4 v[170:171], v[104:107], off offset:512 sc1
	global_store_dwordx4 v[170:171], v[108:111], off offset:576 sc1
	v_pk_mul_f32 v[92:93], v[168:169], v[114:115] op_sel:[1,0]
	v_pk_fma_f32 v[96:97], v[156:157], v[112:113], v[152:153]
	v_pk_fma_f32 v[92:93], v[158:159], v[92:93], v[154:155]
	v_pk_fma_f32 v[78:79], v[142:143], v[78:79], v[138:139]
	v_cndmask_b32_e32 v95, v93, v162, vcc
	v_cndmask_b32_e32 v94, v92, v162, vcc
	v_cndmask_b32_e32 v93, v97, v162, vcc
	v_cndmask_b32_e32 v92, v96, v162, vcc
	v_lshlrev_b64 v[96:97], 12, v[178:179]
	v_lshl_add_u64 v[96:97], s[6:7], 0, v[96:97]
	v_pk_fma_f32 v[76:77], v[140:141], v[76:77], v[136:137]
	v_lshl_add_u64 v[96:97], v[96:97], 0, v[160:161]
	v_cndmask_b32_e32 v79, v79, v162, vcc
	v_cndmask_b32_e32 v78, v78, v162, vcc
	v_cndmask_b32_e32 v77, v77, v162, vcc
	v_cndmask_b32_e32 v76, v76, v162, vcc
	global_store_dwordx4 v[96:97], v[76:79], off offset:512 sc1
	ds_read2_b64 v[76:79], v164 offset0:32 offset1:48
	v_pk_fma_f32 v[66:67], v[130:131], v[66:67], v[134:135]
	v_pk_fma_f32 v[64:65], v[128:129], v[64:65], v[132:133]
	v_pk_fma_f32 v[86:87], v[146:147], v[86:87], v[150:151]
	v_pk_fma_f32 v[84:85], v[144:145], v[84:85], v[148:149]
	v_cndmask_b32_e32 v67, v67, v162, vcc
	v_cndmask_b32_e32 v66, v66, v162, vcc
	v_cndmask_b32_e32 v65, v65, v162, vcc
	v_cndmask_b32_e32 v64, v64, v162, vcc
	v_cndmask_b32_e32 v87, v87, v162, vcc
	v_cndmask_b32_e32 v86, v86, v162, vcc
	v_cndmask_b32_e32 v85, v85, v162, vcc
	v_cndmask_b32_e32 v84, v84, v162, vcc
	global_store_dwordx4 v[96:97], v[64:67], off offset:576 sc1
	global_store_dwordx4 v[96:97], v[84:87], off offset:64 sc1
	s_waitcnt lgkmcnt(0)
	v_sub_f32_e32 v51, v51, v76
	v_sub_f32_e32 v65, v71, v76
	v_sub_f32_e32 v64, v70, v76
	v_sub_f32_e32 v67, v69, v76
	v_sub_f32_e32 v66, v68, v76
	v_add_u32_e32 v84, v163, v177
	v_pk_mul_f32 v[66:67], v[76:77], v[66:67] op_sel:[1,0]
	v_pk_mul_f32 v[64:65], v[76:77], v[64:65] op_sel:[1,0]
	v_ashrrev_i32_e32 v85, 31, v84
	v_pk_fma_f32 v[64:65], v[158:159], v[64:65], v[154:155]
	v_pk_fma_f32 v[68:69], v[156:157], v[66:67], v[152:153]
	v_sub_f32_e32 v50, v50, v76
	v_sub_f32_e32 v49, v49, v76
	v_sub_f32_e32 v48, v48, v76
	v_cndmask_b32_e32 v67, v65, v162, vcc
	v_cndmask_b32_e32 v66, v64, v162, vcc
	v_cndmask_b32_e32 v65, v69, v162, vcc
	v_cndmask_b32_e32 v64, v68, v162, vcc
	v_lshlrev_b64 v[68:69], 12, v[84:85]
	v_pk_mul_f32 v[48:49], v[76:77], v[48:49] op_sel:[1,0]
	v_pk_mul_f32 v[50:51], v[76:77], v[50:51] op_sel:[1,0]
	v_lshl_add_u64 v[68:69], s[6:7], 0, v[68:69]
	v_sub_f32_e32 v63, v63, v76
	v_sub_f32_e32 v62, v62, v76
	v_sub_f32_e32 v61, v61, v76
	v_sub_f32_e32 v60, v60, v76
	v_pk_fma_f32 v[50:51], v[142:143], v[50:51], v[138:139]
	v_pk_fma_f32 v[48:49], v[140:141], v[48:49], v[136:137]
	v_lshl_add_u64 v[68:69], v[68:69], 0, v[160:161]
	v_pk_mul_f32 v[60:61], v[76:77], v[60:61] op_sel:[1,0]
	v_pk_mul_f32 v[62:63], v[76:77], v[62:63] op_sel:[1,0]
	v_cndmask_b32_e32 v51, v51, v162, vcc
	v_cndmask_b32_e32 v50, v50, v162, vcc
	v_cndmask_b32_e32 v49, v49, v162, vcc
	v_cndmask_b32_e32 v48, v48, v162, vcc
	v_pk_fma_f32 v[62:63], v[146:147], v[62:63], v[150:151]
	v_pk_fma_f32 v[60:61], v[144:145], v[60:61], v[148:149]
	global_store_dwordx4 v[68:69], v[48:51], off offset:512 sc1
	v_cndmask_b32_e32 v63, v63, v162, vcc
	v_cndmask_b32_e32 v62, v62, v162, vcc
	v_sub_f32_e32 v49, v123, v76
	v_sub_f32_e32 v48, v122, v76
	v_sub_f32_e32 v51, v121, v76
	v_sub_f32_e32 v50, v120, v76
	v_cndmask_b32_e32 v61, v61, v162, vcc
	v_cndmask_b32_e32 v60, v60, v162, vcc
	v_pk_mul_f32 v[50:51], v[76:77], v[50:51] op_sel:[1,0]
	v_pk_mul_f32 v[48:49], v[76:77], v[48:49] op_sel:[1,0]
	global_store_dwordx4 v[68:69], v[60:63], off offset:64 sc1
	v_pk_fma_f32 v[48:49], v[130:131], v[48:49], v[134:135]
	global_store_dwordx4 v[68:69], v[64:67], off sc1
	v_pk_fma_f32 v[60:61], v[128:129], v[50:51], v[132:133]
	v_cndmask_b32_e32 v51, v49, v162, vcc
	v_cndmask_b32_e32 v50, v48, v162, vcc
	v_cndmask_b32_e32 v49, v61, v162, vcc
	v_cndmask_b32_e32 v48, v60, v162, vcc
	v_add_u32_e32 v60, v163, v176
	global_store_dwordx4 v[68:69], v[48:51], off offset:576 sc1
	v_ashrrev_i32_e32 v61, 31, v60
	v_lshlrev_b64 v[60:61], 12, v[60:61]
	v_sub_f32_e32 v49, v127, v78
	v_sub_f32_e32 v48, v126, v78
	v_sub_f32_e32 v51, v125, v78
	v_sub_f32_e32 v50, v124, v78
	v_pk_mul_f32 v[50:51], v[78:79], v[50:51] op_sel:[1,0]
	v_pk_mul_f32 v[48:49], v[78:79], v[48:49] op_sel:[1,0]
	v_pk_fma_f32 v[62:63], v[156:157], v[50:51], v[152:153]
	v_pk_fma_f32 v[48:49], v[158:159], v[48:49], v[154:155]
	v_lshl_add_u64 v[60:61], s[6:7], 0, v[60:61]
	v_cndmask_b32_e32 v51, v49, v162, vcc
	v_cndmask_b32_e32 v50, v48, v162, vcc
	v_cndmask_b32_e32 v49, v63, v162, vcc
	v_cndmask_b32_e32 v48, v62, v162, vcc
	v_lshl_add_u64 v[64:65], v[60:61], 0, v[160:161]
	global_store_dwordx4 v[64:65], v[48:51], off sc1
	global_store_dwordx4 v[96:97], v[92:95], off sc1
	s_nop 0
	v_sub_f32_e32 v49, v119, v78
	v_sub_f32_e32 v48, v118, v78
	v_sub_f32_e32 v51, v117, v78
	v_sub_f32_e32 v50, v116, v78
	v_pk_mul_f32 v[50:51], v[78:79], v[50:51] op_sel:[1,0]
	v_pk_mul_f32 v[48:49], v[78:79], v[48:49] op_sel:[1,0]
	v_pk_fma_f32 v[60:61], v[144:145], v[50:51], v[148:149]
	v_pk_fma_f32 v[48:49], v[146:147], v[48:49], v[150:151]
	s_nop 0
	v_cndmask_b32_e32 v51, v49, v162, vcc
	v_cndmask_b32_e32 v50, v48, v162, vcc
	v_cndmask_b32_e32 v49, v61, v162, vcc
	v_cndmask_b32_e32 v48, v60, v162, vcc
	global_store_dwordx4 v[64:65], v[48:51], off offset:64 sc1
	s_nop 1
	v_sub_f32_e32 v49, v103, v78
	v_sub_f32_e32 v48, v102, v78
	v_sub_f32_e32 v51, v101, v78
	v_sub_f32_e32 v50, v100, v78
	v_pk_mul_f32 v[50:51], v[78:79], v[50:51] op_sel:[1,0]
	v_pk_mul_f32 v[48:49], v[78:79], v[48:49] op_sel:[1,0]
	v_pk_fma_f32 v[60:61], v[140:141], v[50:51], v[136:137]
	v_pk_fma_f32 v[48:49], v[142:143], v[48:49], v[138:139]
	s_nop 0
	v_cndmask_b32_e32 v51, v49, v162, vcc
	v_cndmask_b32_e32 v50, v48, v162, vcc
	v_cndmask_b32_e32 v49, v61, v162, vcc
	v_cndmask_b32_e32 v48, v60, v162, vcc
	global_store_dwordx4 v[64:65], v[48:51], off offset:512 sc1
	ds_read2_b64 v[60:63], v164 offset0:128 offset1:144
	s_waitcnt lgkmcnt(0)
	v_sub_f32_e32 v39, v39, v62
	v_sub_f32_e32 v49, v91, v78
	v_sub_f32_e32 v48, v90, v78
	v_sub_f32_e32 v51, v89, v78
	v_sub_f32_e32 v50, v88, v78
	v_pk_mul_f32 v[50:51], v[78:79], v[50:51] op_sel:[1,0]
	v_pk_mul_f32 v[48:49], v[78:79], v[48:49] op_sel:[1,0]
	v_pk_fma_f32 v[66:67], v[128:129], v[50:51], v[132:133]
	v_pk_fma_f32 v[48:49], v[130:131], v[48:49], v[134:135]
	v_sub_f32_e32 v38, v38, v62
	v_cndmask_b32_e32 v51, v49, v162, vcc
	v_cndmask_b32_e32 v50, v48, v162, vcc
	v_cndmask_b32_e32 v49, v67, v162, vcc
	v_cndmask_b32_e32 v48, v66, v162, vcc
	global_store_dwordx4 v[64:65], v[48:51], off offset:576 sc1
	v_add_u32_e32 v64, v163, v175
	v_ashrrev_i32_e32 v65, 31, v64
	v_sub_f32_e32 v49, v83, v60
	v_sub_f32_e32 v48, v82, v60
	v_sub_f32_e32 v51, v81, v60
	v_sub_f32_e32 v50, v80, v60
	v_pk_mul_f32 v[50:51], v[60:61], v[50:51] op_sel:[1,0]
	v_pk_mul_f32 v[48:49], v[60:61], v[48:49] op_sel:[1,0]
	v_lshlrev_b64 v[64:65], 12, v[64:65]
	v_pk_fma_f32 v[48:49], v[158:159], v[48:49], v[154:155]
	v_pk_fma_f32 v[66:67], v[156:157], v[50:51], v[152:153]
	v_lshl_add_u64 v[64:65], s[6:7], 0, v[64:65]
	v_cndmask_b32_e32 v51, v49, v162, vcc
	v_cndmask_b32_e32 v50, v48, v162, vcc
	v_cndmask_b32_e32 v49, v67, v162, vcc
	v_cndmask_b32_e32 v48, v66, v162, vcc
	v_lshl_add_u64 v[64:65], v[64:65], 0, v[160:161]
	global_store_dwordx4 v[64:65], v[48:51], off sc1
	v_sub_f32_e32 v37, v37, v62
	v_sub_f32_e32 v36, v36, v62
	v_sub_f32_e32 v49, v75, v60
	v_sub_f32_e32 v48, v74, v60
	v_sub_f32_e32 v51, v73, v60
	v_sub_f32_e32 v50, v72, v60
	v_pk_mul_f32 v[50:51], v[60:61], v[50:51] op_sel:[1,0]
	v_pk_mul_f32 v[48:49], v[60:61], v[48:49] op_sel:[1,0]
	v_pk_fma_f32 v[66:67], v[144:145], v[50:51], v[148:149]
	v_pk_fma_f32 v[48:49], v[146:147], v[48:49], v[150:151]
	v_pk_mul_f32 v[36:37], v[62:63], v[36:37] op_sel:[1,0]
	v_cndmask_b32_e32 v51, v49, v162, vcc
	v_cndmask_b32_e32 v50, v48, v162, vcc
	v_cndmask_b32_e32 v49, v67, v162, vcc
	v_cndmask_b32_e32 v48, v66, v162, vcc
	global_store_dwordx4 v[64:65], v[48:51], off offset:64 sc1
	v_pk_mul_f32 v[38:39], v[62:63], v[38:39] op_sel:[1,0]
	v_pk_fma_f32 v[36:37], v[140:141], v[36:37], v[136:137]
	v_sub_f32_e32 v49, v59, v60
	v_sub_f32_e32 v48, v58, v60
	v_sub_f32_e32 v51, v57, v60
	v_sub_f32_e32 v50, v56, v60
	v_pk_mul_f32 v[50:51], v[60:61], v[50:51] op_sel:[1,0]
	v_pk_mul_f32 v[48:49], v[60:61], v[48:49] op_sel:[1,0]
	v_pk_fma_f32 v[56:57], v[140:141], v[50:51], v[136:137]
	v_pk_fma_f32 v[48:49], v[142:143], v[48:49], v[138:139]
	v_pk_fma_f32 v[38:39], v[142:143], v[38:39], v[138:139]
	v_cndmask_b32_e32 v51, v49, v162, vcc
	v_cndmask_b32_e32 v50, v48, v162, vcc
	v_cndmask_b32_e32 v49, v57, v162, vcc
	v_cndmask_b32_e32 v48, v56, v162, vcc
	global_store_dwordx4 v[64:65], v[48:51], off offset:512 sc1
	v_cndmask_b32_e32 v39, v39, v162, vcc
	v_cndmask_b32_e32 v38, v38, v162, vcc
	v_add_u32_e32 v48, v163, v174
	v_ashrrev_i32_e32 v49, 31, v48
	v_lshlrev_b64 v[48:49], 12, v[48:49]
	v_lshl_add_u64 v[48:49], s[6:7], 0, v[48:49]
	v_lshl_add_u64 v[48:49], v[48:49], 0, v[160:161]
	v_cndmask_b32_e32 v37, v37, v162, vcc
	v_cndmask_b32_e32 v36, v36, v162, vcc
	global_store_dwordx4 v[48:49], v[36:39], off offset:512 sc1
	ds_read2_b64 v[36:39], v164 offset0:160 offset1:176
	v_sub_f32_e32 v31, v31, v62
	v_sub_f32_e32 v30, v30, v62
	v_sub_f32_e32 v29, v29, v62
	v_sub_f32_e32 v28, v28, v62
	v_sub_f32_e32 v43, v43, v62
	v_sub_f32_e32 v42, v42, v62
	v_sub_f32_e32 v41, v41, v62
	v_sub_f32_e32 v40, v40, v62
	v_pk_mul_f32 v[28:29], v[62:63], v[28:29] op_sel:[1,0]
	v_pk_mul_f32 v[30:31], v[62:63], v[30:31] op_sel:[1,0]
	v_pk_mul_f32 v[40:41], v[62:63], v[40:41] op_sel:[1,0]
	v_pk_mul_f32 v[42:43], v[62:63], v[42:43] op_sel:[1,0]
	v_pk_fma_f32 v[30:31], v[130:131], v[30:31], v[134:135]
	v_pk_fma_f32 v[28:29], v[128:129], v[28:29], v[132:133]
	v_pk_fma_f32 v[42:43], v[146:147], v[42:43], v[150:151]
	v_pk_fma_f32 v[40:41], v[144:145], v[40:41], v[148:149]
	v_cndmask_b32_e32 v31, v31, v162, vcc
	v_cndmask_b32_e32 v30, v30, v162, vcc
	v_cndmask_b32_e32 v29, v29, v162, vcc
	v_cndmask_b32_e32 v28, v28, v162, vcc
	v_cndmask_b32_e32 v43, v43, v162, vcc
	v_cndmask_b32_e32 v42, v42, v162, vcc
	v_cndmask_b32_e32 v41, v41, v162, vcc
	v_cndmask_b32_e32 v40, v40, v162, vcc
	global_store_dwordx4 v[48:49], v[28:31], off offset:576 sc1
	global_store_dwordx4 v[48:49], v[40:43], off offset:64 sc1
	s_waitcnt lgkmcnt(0)
	v_sub_f32_e32 v15, v15, v36
	v_sub_f32_e32 v29, v35, v36
	v_sub_f32_e32 v28, v34, v36
	v_sub_f32_e32 v31, v33, v36
	v_sub_f32_e32 v30, v32, v36
	v_add_u32_e32 v40, v163, v173
	v_pk_mul_f32 v[30:31], v[36:37], v[30:31] op_sel:[1,0]
	v_pk_mul_f32 v[28:29], v[36:37], v[28:29] op_sel:[1,0]
	v_ashrrev_i32_e32 v41, 31, v40
	v_pk_fma_f32 v[28:29], v[158:159], v[28:29], v[154:155]
	v_pk_fma_f32 v[32:33], v[156:157], v[30:31], v[152:153]
	v_sub_f32_e32 v14, v14, v36
	v_sub_f32_e32 v13, v13, v36
	v_sub_f32_e32 v12, v12, v36
	v_cndmask_b32_e32 v31, v29, v162, vcc
	v_cndmask_b32_e32 v30, v28, v162, vcc
	v_cndmask_b32_e32 v29, v33, v162, vcc
	v_cndmask_b32_e32 v28, v32, v162, vcc
	v_lshlrev_b64 v[32:33], 12, v[40:41]
	v_sub_f32_e32 v23, v23, v36
	v_sub_f32_e32 v22, v22, v36
	v_sub_f32_e32 v21, v21, v36
	v_sub_f32_e32 v20, v20, v36
	v_pk_mul_f32 v[12:13], v[36:37], v[12:13] op_sel:[1,0]
	v_pk_mul_f32 v[14:15], v[36:37], v[14:15] op_sel:[1,0]
	v_sub_f32_e32 v47, v47, v60
	v_sub_f32_e32 v46, v46, v60
	v_sub_f32_e32 v45, v45, v60
	v_sub_f32_e32 v44, v44, v60
	v_lshl_add_u64 v[32:33], s[6:7], 0, v[32:33]
	v_pk_mul_f32 v[20:21], v[36:37], v[20:21] op_sel:[1,0]
	v_pk_mul_f32 v[22:23], v[36:37], v[22:23] op_sel:[1,0]
	v_pk_fma_f32 v[14:15], v[130:131], v[14:15], v[134:135]
	v_pk_fma_f32 v[12:13], v[128:129], v[12:13], v[132:133]
	v_pk_mul_f32 v[44:45], v[60:61], v[44:45] op_sel:[1,0]
	v_pk_mul_f32 v[46:47], v[60:61], v[46:47] op_sel:[1,0]
	v_lshl_add_u64 v[32:33], v[32:33], 0, v[160:161]
	v_pk_fma_f32 v[22:23], v[142:143], v[22:23], v[138:139]
	v_pk_fma_f32 v[20:21], v[140:141], v[20:21], v[136:137]
	v_cndmask_b32_e32 v15, v15, v162, vcc
	v_cndmask_b32_e32 v14, v14, v162, vcc
	v_cndmask_b32_e32 v13, v13, v162, vcc
	v_cndmask_b32_e32 v12, v12, v162, vcc
	v_pk_fma_f32 v[46:47], v[130:131], v[46:47], v[134:135]
	v_pk_fma_f32 v[44:45], v[128:129], v[44:45], v[132:133]
	v_cndmask_b32_e32 v23, v23, v162, vcc
	v_cndmask_b32_e32 v22, v22, v162, vcc
	v_cndmask_b32_e32 v21, v21, v162, vcc
	v_cndmask_b32_e32 v20, v20, v162, vcc
	global_store_dwordx4 v[32:33], v[12:15], off offset:576 sc1
	v_cndmask_b32_e32 v47, v47, v162, vcc
	v_cndmask_b32_e32 v46, v46, v162, vcc
	v_sub_f32_e32 v13, v19, v38
	v_sub_f32_e32 v12, v18, v38
	v_sub_f32_e32 v15, v17, v38
	v_sub_f32_e32 v14, v16, v38
	v_cndmask_b32_e32 v45, v45, v162, vcc
	v_cndmask_b32_e32 v44, v44, v162, vcc
	global_store_dwordx4 v[32:33], v[20:23], off offset:512 sc1
	v_pk_mul_f32 v[14:15], v[38:39], v[14:15] op_sel:[1,0]
	v_pk_mul_f32 v[12:13], v[38:39], v[12:13] op_sel:[1,0]
	v_add_u32_e32 v20, v163, v172
	global_store_dwordx4 v[64:65], v[44:47], off offset:576 sc1
	v_sub_f32_e32 v27, v27, v36
	v_sub_f32_e32 v26, v26, v36
	v_sub_f32_e32 v45, v55, v62
	v_sub_f32_e32 v44, v54, v62
	v_sub_f32_e32 v47, v53, v62
	v_sub_f32_e32 v46, v52, v62
	v_sub_f32_e32 v25, v25, v36
	v_sub_f32_e32 v24, v24, v36
	v_ashrrev_i32_e32 v21, 31, v20
	v_pk_fma_f32 v[12:13], v[158:159], v[12:13], v[154:155]
	v_pk_fma_f32 v[16:17], v[156:157], v[14:15], v[152:153]
	v_sub_f32_e32 v11, v11, v38
	v_sub_f32_e32 v10, v10, v38
	v_sub_f32_e32 v9, v9, v38
	v_sub_f32_e32 v8, v8, v38
	v_sub_f32_e32 v7, v7, v38
	v_sub_f32_e32 v6, v6, v38
	v_sub_f32_e32 v5, v5, v38
	v_sub_f32_e32 v4, v4, v38
	v_sub_f32_e32 v3, v3, v38
	v_sub_f32_e32 v2, v2, v38
	v_sub_f32_e32 v1, v1, v38
	v_sub_f32_e32 v0, v0, v38
	v_pk_mul_f32 v[46:47], v[62:63], v[46:47] op_sel:[1,0]
	v_pk_mul_f32 v[44:45], v[62:63], v[44:45] op_sel:[1,0]
	v_pk_mul_f32 v[24:25], v[36:37], v[24:25] op_sel:[1,0]
	v_pk_mul_f32 v[26:27], v[36:37], v[26:27] op_sel:[1,0]
	v_cndmask_b32_e32 v15, v13, v162, vcc
	v_cndmask_b32_e32 v14, v12, v162, vcc
	v_cndmask_b32_e32 v13, v17, v162, vcc
	v_cndmask_b32_e32 v12, v16, v162, vcc
	v_lshlrev_b64 v[16:17], 12, v[20:21]
	v_pk_mul_f32 v[8:9], v[38:39], v[8:9] op_sel:[1,0]
	v_pk_mul_f32 v[10:11], v[38:39], v[10:11] op_sel:[1,0]
	v_pk_mul_f32 v[4:5], v[38:39], v[4:5] op_sel:[1,0]
	v_pk_mul_f32 v[6:7], v[38:39], v[6:7] op_sel:[1,0]
	v_pk_mul_f32 v[0:1], v[38:39], v[0:1] op_sel:[1,0]
	v_pk_mul_f32 v[2:3], v[38:39], v[2:3] op_sel:[1,0]
	v_pk_fma_f32 v[44:45], v[158:159], v[44:45], v[154:155]
	v_pk_fma_f32 v[50:51], v[156:157], v[46:47], v[152:153]
	v_pk_fma_f32 v[26:27], v[146:147], v[26:27], v[150:151]
	v_pk_fma_f32 v[24:25], v[144:145], v[24:25], v[148:149]
	v_lshl_add_u64 v[16:17], s[6:7], 0, v[16:17]
	v_pk_fma_f32 v[10:11], v[146:147], v[10:11], v[150:151]
	v_pk_fma_f32 v[8:9], v[144:145], v[8:9], v[148:149]
	v_pk_fma_f32 v[6:7], v[142:143], v[6:7], v[138:139]
	v_pk_fma_f32 v[4:5], v[140:141], v[4:5], v[136:137]
	v_pk_fma_f32 v[2:3], v[130:131], v[2:3], v[134:135]
	v_pk_fma_f32 v[0:1], v[128:129], v[0:1], v[132:133]
	v_cndmask_b32_e32 v47, v45, v162, vcc
	v_cndmask_b32_e32 v46, v44, v162, vcc
	v_cndmask_b32_e32 v45, v51, v162, vcc
	v_cndmask_b32_e32 v44, v50, v162, vcc
	v_cndmask_b32_e32 v27, v27, v162, vcc
	v_cndmask_b32_e32 v26, v26, v162, vcc
	v_cndmask_b32_e32 v25, v25, v162, vcc
	v_cndmask_b32_e32 v24, v24, v162, vcc
	v_lshl_add_u64 v[16:17], v[16:17], 0, v[160:161]
	v_cndmask_b32_e32 v11, v11, v162, vcc
	v_cndmask_b32_e32 v10, v10, v162, vcc
	v_cndmask_b32_e32 v9, v9, v162, vcc
	v_cndmask_b32_e32 v8, v8, v162, vcc
	v_cndmask_b32_e32 v7, v7, v162, vcc
	v_cndmask_b32_e32 v6, v6, v162, vcc
	v_cndmask_b32_e32 v5, v5, v162, vcc
	v_cndmask_b32_e32 v4, v4, v162, vcc
	v_cndmask_b32_e32 v3, v3, v162, vcc
	v_cndmask_b32_e32 v2, v2, v162, vcc
	v_cndmask_b32_e32 v1, v1, v162, vcc
	v_cndmask_b32_e32 v0, v0, v162, vcc
	global_store_dwordx4 v[48:49], v[44:47], off sc1
	global_store_dwordx4 v[32:33], v[28:31], off sc1
	global_store_dwordx4 v[32:33], v[24:27], off offset:64 sc1
	global_store_dwordx4 v[16:17], v[12:15], off sc1
	global_store_dwordx4 v[16:17], v[8:11], off offset:64 sc1
	global_store_dwordx4 v[16:17], v[4:7], off offset:512 sc1
	global_store_dwordx4 v[16:17], v[0:3], off offset:576 sc1
